# P3: conv loop rewritten by hand with the next token's tap loads in flight (scalar tap bases, border taps skipped); on top of the P4 copy-path change
# speedup vs baseline: 1.0162x; 1.0098x over previous
.Lcv_entry:
	v_and_b32_e32 v194, 0xff, v79
	v_lshlrev_b32_e32 v195, 5, v194
	v_lshlrev_b32_e32 v194, 4, v194
	s_mov_b64 s[8:9], s[78:79]
	global_load_dwordx4 v[0:3], v195, s[8:9]
	global_load_dwordx4 v[4:7], v195, s[8:9] offset:16
	s_add_u32 s8, s8, 0x2000
	s_addc_u32 s9, s9, 0
	global_load_dwordx4 v[8:11], v195, s[8:9]
	global_load_dwordx4 v[12:15], v195, s[8:9] offset:16
	s_add_u32 s8, s8, 0x2000
	s_addc_u32 s9, s9, 0
	global_load_dwordx4 v[16:19], v195, s[8:9]
	global_load_dwordx4 v[20:23], v195, s[8:9] offset:16
	s_add_u32 s8, s8, 0x2000
	s_addc_u32 s9, s9, 0
	global_load_dwordx4 v[24:27], v195, s[8:9]
	global_load_dwordx4 v[28:31], v195, s[8:9] offset:16
	s_add_u32 s8, s8, 0x2000
	s_addc_u32 s9, s9, 0
	global_load_dwordx4 v[32:35], v195, s[8:9]
	global_load_dwordx4 v[36:39], v195, s[8:9] offset:16
	s_add_u32 s8, s8, 0x2000
	s_addc_u32 s9, s9, 0
	global_load_dwordx4 v[40:43], v195, s[8:9]
	global_load_dwordx4 v[44:47], v195, s[8:9] offset:16
	s_add_u32 s8, s8, 0x2000
	s_addc_u32 s9, s9, 0
	global_load_dwordx4 v[48:51], v195, s[8:9]
	global_load_dwordx4 v[52:55], v195, s[8:9] offset:16
	s_add_u32 s8, s8, 0x2000
	s_addc_u32 s9, s9, 0
	global_load_dwordx4 v[56:59], v195, s[8:9]
	global_load_dwordx4 v[60:63], v195, s[8:9] offset:16
	s_add_u32 s8, s8, 0x2000
	s_addc_u32 s9, s9, 0
	global_load_dwordx4 v[64:67], v195, s[8:9]
	global_load_dwordx4 v[68:71], v195, s[8:9] offset:16
	v_readlane_b32 s10, v254, 26
	v_readlane_b32 s11, v254, 27
	v_readfirstlane_b32 s6, v79
	s_nop 3
	global_load_dwordx4 v[112:115], v195, s[10:11]
	global_load_dwordx4 v[116:119], v195, s[10:11] offset:16
	s_lshr_b32 s6, s6, 8
	s_lshl_b32 s16, s2, 1
	s_add_u32 s16, s16, s6
	s_mov_b32 s17, s16
	s_add_u32 s0, s28, 0x8502000
	s_addc_u32 s1, s29, 0
	s_add_u32 s4, s28, 0xe500000
	s_addc_u32 s5, s29, 0
	s_movk_i32 s48, 0x3000
	s_mov_b32 s27, 0xc3000
	s_and_b32 s20, s16, 0xff
	s_mov_b32 s18, 0x38
	s_cmp_eq_u32 s20, 0
	s_cselect_b32 s21, 8, 0
	s_andn2_b32 s18, s18, s21
	s_cmp_eq_u32 s20, 0xff
	s_cselect_b32 s21, 32, 0
	s_andn2_b32 s18, s18, s21
	s_mul_i32 s22, s16, 0x3000
	s_mul_hi_u32 s23, s16, 0x3000
	s_add_u32 s22, s0, s22
	s_addc_u32 s23, s1, s23
	s_sub_u32 s22, s22, 0x3000
	s_subb_u32 s23, s23, 0
	s_bitcmp1_b32 s18, 3
	s_cselect_b32 s24, 0x0, s48
	s_add_u32 s80, s22, s24
	s_addc_u32 s81, s23, 0
	global_load_dwordx4 v[196:199], v194, s[80:81]
	s_bitcmp1_b32 s18, 4
	s_cselect_b32 s24, 0x3000, s48
	s_add_u32 s82, s22, s24
	s_addc_u32 s83, s23, 0
	global_load_dwordx4 v[200:203], v194, s[82:83]
	s_bitcmp1_b32 s18, 5
	s_cselect_b32 s24, 0x6000, s48
	s_add_u32 s84, s22, s24
	s_addc_u32 s85, s23, 0
	global_load_dwordx4 v[204:207], v194, s[84:85]
	s_add_u32 s16, s16, 0x200
	s_waitcnt vmcnt(3)
	s_and_b32 s20, s16, 0xff
	s_mov_b32 s19, 0x38
	s_cmp_eq_u32 s20, 0
	s_cselect_b32 s21, 8, 0
	s_andn2_b32 s19, s19, s21
	s_cmp_eq_u32 s20, 0xff
	s_cselect_b32 s21, 32, 0
	s_andn2_b32 s19, s19, s21
	s_mul_i32 s22, s16, 0x3000
	s_mul_hi_u32 s23, s16, 0x3000
	s_add_u32 s22, s0, s22
	s_addc_u32 s23, s1, s23
	s_sub_u32 s22, s22, 0x3000
	s_subb_u32 s23, s23, 0
	s_bitcmp1_b32 s19, 3
	s_cselect_b32 s24, 0x0, s48
	s_add_u32 s80, s22, s24
	s_addc_u32 s81, s23, 0
	global_load_dwordx4 v[208:211], v194, s[80:81]
	s_bitcmp1_b32 s19, 4
	s_cselect_b32 s24, 0x3000, s48
	s_add_u32 s82, s22, s24
	s_addc_u32 s83, s23, 0
	global_load_dwordx4 v[212:215], v194, s[82:83]
	s_bitcmp1_b32 s19, 5
	s_cselect_b32 s24, 0x6000, s48
	s_add_u32 s84, s22, s24
	s_addc_u32 s85, s23, 0
	global_load_dwordx4 v[216:219], v194, s[84:85]
	s_add_u32 s16, s16, 0x200
	s_waitcnt vmcnt(3)
	v_mov_b32_e32 v80, v112
	v_mov_b32_e32 v81, v113
	v_mov_b32_e32 v82, v114
	v_mov_b32_e32 v83, v115
	v_mov_b32_e32 v84, v116
	v_mov_b32_e32 v85, v117
	v_mov_b32_e32 v86, v118
	v_mov_b32_e32 v87, v119
	s_bitcmp0_b32 s18, 3
	s_cbranch_scc1 .Lcv_skip_1
	v_lshlrev_b32_e32 v88, 16, v196
	v_and_b32_e32 v89, 0xffff0000, v196
	v_lshlrev_b32_e32 v90, 16, v197
	v_and_b32_e32 v91, 0xffff0000, v197
	v_lshlrev_b32_e32 v92, 16, v198
	v_and_b32_e32 v93, 0xffff0000, v198
	v_lshlrev_b32_e32 v94, 16, v199
	v_and_b32_e32 v95, 0xffff0000, v199
	v_fmac_f32_e32 v80, v24, v88
	v_fmac_f32_e32 v81, v25, v89
	v_fmac_f32_e32 v82, v26, v90
	v_fmac_f32_e32 v83, v27, v91
	v_fmac_f32_e32 v84, v28, v92
	v_fmac_f32_e32 v85, v29, v93
	v_fmac_f32_e32 v86, v30, v94
	v_fmac_f32_e32 v87, v31, v95
.Lcv_skip_1:
	s_bitcmp0_b32 s18, 4
	s_cbranch_scc1 .Lcv_skip_2
	v_lshlrev_b32_e32 v88, 16, v200
	v_and_b32_e32 v89, 0xffff0000, v200
	v_lshlrev_b32_e32 v90, 16, v201
	v_and_b32_e32 v91, 0xffff0000, v201
	v_lshlrev_b32_e32 v92, 16, v202
	v_and_b32_e32 v93, 0xffff0000, v202
	v_lshlrev_b32_e32 v94, 16, v203
	v_and_b32_e32 v95, 0xffff0000, v203
	v_fmac_f32_e32 v80, v32, v88
	v_fmac_f32_e32 v81, v33, v89
	v_fmac_f32_e32 v82, v34, v90
	v_fmac_f32_e32 v83, v35, v91
	v_fmac_f32_e32 v84, v36, v92
	v_fmac_f32_e32 v85, v37, v93
	v_fmac_f32_e32 v86, v38, v94
	v_fmac_f32_e32 v87, v39, v95
.Lcv_skip_2:
	s_bitcmp0_b32 s18, 5
	s_cbranch_scc1 .Lcv_skip_3
	v_lshlrev_b32_e32 v88, 16, v204
	v_and_b32_e32 v89, 0xffff0000, v204
	v_lshlrev_b32_e32 v90, 16, v205
	v_and_b32_e32 v91, 0xffff0000, v205
	v_lshlrev_b32_e32 v92, 16, v206
	v_and_b32_e32 v93, 0xffff0000, v206
	v_lshlrev_b32_e32 v94, 16, v207
	v_and_b32_e32 v95, 0xffff0000, v207
	v_fmac_f32_e32 v80, v40, v88
	v_fmac_f32_e32 v81, v41, v89
	v_fmac_f32_e32 v82, v42, v90
	v_fmac_f32_e32 v83, v43, v91
	v_fmac_f32_e32 v84, v44, v92
	v_fmac_f32_e32 v85, v45, v93
	v_fmac_f32_e32 v86, v46, v94
	v_fmac_f32_e32 v87, v47, v95
.Lcv_skip_3:
	v_mul_f32_e32 v93, 0xbfb8aa3b, v80
	v_exp_f32_e32 v93, v93
	s_nop 0
	v_add_f32_e32 v88, 1.0, v93
	v_div_scale_f32 v89, s[12:13], v88, v88, v80
	v_rcp_f32_e32 v90, v89
	s_nop 0
	v_fma_f32 v93, -v89, v90, 1.0
	v_fmac_f32_e32 v90, v93, v90
	v_div_scale_f32 v91, vcc, v80, v88, v80
	v_mul_f32_e32 v92, v91, v90
	v_fma_f32 v93, -v89, v92, v91
	v_fmac_f32_e32 v92, v93, v90
	v_fma_f32 v91, -v89, v92, v91
	v_div_fmas_f32 v91, v91, v90, v92
	v_div_fixup_f32 v91, v91, v88, v80
	v_mul_f32_e32 v99, 0xbfb8aa3b, v81
	v_exp_f32_e32 v99, v99
	s_nop 0
	v_add_f32_e32 v94, 1.0, v99
	v_div_scale_f32 v95, s[12:13], v94, v94, v81
	v_rcp_f32_e32 v96, v95
	s_nop 0
	v_fma_f32 v99, -v95, v96, 1.0
	v_fmac_f32_e32 v96, v99, v96
	v_div_scale_f32 v97, vcc, v81, v94, v81
	v_mul_f32_e32 v98, v97, v96
	v_fma_f32 v99, -v95, v98, v97
	v_fmac_f32_e32 v98, v99, v96
	v_fma_f32 v97, -v95, v98, v97
	v_div_fmas_f32 v97, v97, v96, v98
	v_div_fixup_f32 v97, v97, v94, v81
	v_cvt_pk_bf16_f32 v104, v91, v97
	v_mul_f32_e32 v93, 0xbfb8aa3b, v82
	v_exp_f32_e32 v93, v93
	s_nop 0
	v_add_f32_e32 v88, 1.0, v93
	v_div_scale_f32 v89, s[12:13], v88, v88, v82
	v_rcp_f32_e32 v90, v89
	s_nop 0
	v_fma_f32 v93, -v89, v90, 1.0
	v_fmac_f32_e32 v90, v93, v90
	v_div_scale_f32 v91, vcc, v82, v88, v82
	v_mul_f32_e32 v92, v91, v90
	v_fma_f32 v93, -v89, v92, v91
	v_fmac_f32_e32 v92, v93, v90
	v_fma_f32 v91, -v89, v92, v91
	v_div_fmas_f32 v91, v91, v90, v92
	v_div_fixup_f32 v91, v91, v88, v82
	v_mul_f32_e32 v99, 0xbfb8aa3b, v83
	v_exp_f32_e32 v99, v99
	s_nop 0
	v_add_f32_e32 v94, 1.0, v99
	v_div_scale_f32 v95, s[12:13], v94, v94, v83
	v_rcp_f32_e32 v96, v95
	s_nop 0
	v_fma_f32 v99, -v95, v96, 1.0
	v_fmac_f32_e32 v96, v99, v96
	v_div_scale_f32 v97, vcc, v83, v94, v83
	v_mul_f32_e32 v98, v97, v96
	v_fma_f32 v99, -v95, v98, v97
	v_fmac_f32_e32 v98, v99, v96
	v_fma_f32 v97, -v95, v98, v97
	v_div_fmas_f32 v97, v97, v96, v98
	v_div_fixup_f32 v97, v97, v94, v83
	v_cvt_pk_bf16_f32 v105, v91, v97
	v_mul_f32_e32 v93, 0xbfb8aa3b, v84
	v_exp_f32_e32 v93, v93
	s_nop 0
	v_add_f32_e32 v88, 1.0, v93
	v_div_scale_f32 v89, s[12:13], v88, v88, v84
	v_rcp_f32_e32 v90, v89
	s_nop 0
	v_fma_f32 v93, -v89, v90, 1.0
	v_fmac_f32_e32 v90, v93, v90
	v_div_scale_f32 v91, vcc, v84, v88, v84
	v_mul_f32_e32 v92, v91, v90
	v_fma_f32 v93, -v89, v92, v91
	v_fmac_f32_e32 v92, v93, v90
	v_fma_f32 v91, -v89, v92, v91
	v_div_fmas_f32 v91, v91, v90, v92
	v_div_fixup_f32 v91, v91, v88, v84
	v_mul_f32_e32 v99, 0xbfb8aa3b, v85
	v_exp_f32_e32 v99, v99
	s_nop 0
	v_add_f32_e32 v94, 1.0, v99
	v_div_scale_f32 v95, s[12:13], v94, v94, v85
	v_rcp_f32_e32 v96, v95
	s_nop 0
	v_fma_f32 v99, -v95, v96, 1.0
	v_fmac_f32_e32 v96, v99, v96
	v_div_scale_f32 v97, vcc, v85, v94, v85
	v_mul_f32_e32 v98, v97, v96
	v_fma_f32 v99, -v95, v98, v97
	v_fmac_f32_e32 v98, v99, v96
	v_fma_f32 v97, -v95, v98, v97
	v_div_fmas_f32 v97, v97, v96, v98
	v_div_fixup_f32 v97, v97, v94, v85
	v_cvt_pk_bf16_f32 v106, v91, v97
	v_mul_f32_e32 v93, 0xbfb8aa3b, v86
	v_exp_f32_e32 v93, v93
	s_nop 0
	v_add_f32_e32 v88, 1.0, v93
	v_div_scale_f32 v89, s[12:13], v88, v88, v86
	v_rcp_f32_e32 v90, v89
	s_nop 0
	v_fma_f32 v93, -v89, v90, 1.0
	v_fmac_f32_e32 v90, v93, v90
	v_div_scale_f32 v91, vcc, v86, v88, v86
	v_mul_f32_e32 v92, v91, v90
	v_fma_f32 v93, -v89, v92, v91
	v_fmac_f32_e32 v92, v93, v90
	v_fma_f32 v91, -v89, v92, v91
	v_div_fmas_f32 v91, v91, v90, v92
	v_div_fixup_f32 v91, v91, v88, v86
	v_mul_f32_e32 v99, 0xbfb8aa3b, v87
	v_exp_f32_e32 v99, v99
	s_nop 0
	v_add_f32_e32 v94, 1.0, v99
	v_div_scale_f32 v95, s[12:13], v94, v94, v87
	v_rcp_f32_e32 v96, v95
	s_nop 0
	v_fma_f32 v99, -v95, v96, 1.0
	v_fmac_f32_e32 v96, v99, v96
	v_div_scale_f32 v97, vcc, v87, v94, v87
	v_mul_f32_e32 v98, v97, v96
	v_fma_f32 v99, -v95, v98, v97
	v_fmac_f32_e32 v98, v99, v96
	v_fma_f32 v97, -v95, v98, v97
	v_div_fmas_f32 v97, v97, v96, v98
	v_div_fixup_f32 v97, v97, v94, v87
	v_cvt_pk_bf16_f32 v107, v91, v97
	s_lshl_b32 s22, s17, 12
	s_add_u32 s22, s4, s22
	s_addc_u32 s23, s5, 0
	s_add_u32 s17, s17, 0x200
	global_store_dwordx4 v194, v[104:107], s[22:23]
	s_and_b32 s20, s16, 0xff
	s_mov_b32 s18, 0x38
	s_cmp_eq_u32 s20, 0
	s_cselect_b32 s21, 8, 0
	s_andn2_b32 s18, s18, s21
	s_cmp_eq_u32 s20, 0xff
	s_cselect_b32 s21, 32, 0
	s_andn2_b32 s18, s18, s21
	s_mul_i32 s22, s16, 0x3000
	s_mul_hi_u32 s23, s16, 0x3000
	s_add_u32 s22, s0, s22
	s_addc_u32 s23, s1, s23
	s_sub_u32 s22, s22, 0x3000
	s_subb_u32 s23, s23, 0
	s_bitcmp1_b32 s18, 3
	s_cselect_b32 s24, 0x0, s48
	s_add_u32 s80, s22, s24
	s_addc_u32 s81, s23, 0
	global_load_dwordx4 v[196:199], v194, s[80:81]
	s_bitcmp1_b32 s18, 4
	s_cselect_b32 s24, 0x3000, s48
	s_add_u32 s82, s22, s24
	s_addc_u32 s83, s23, 0
	global_load_dwordx4 v[200:203], v194, s[82:83]
	s_bitcmp1_b32 s18, 5
	s_cselect_b32 s24, 0x6000, s48
	s_add_u32 s84, s22, s24
	s_addc_u32 s85, s23, 0
	global_load_dwordx4 v[204:207], v194, s[84:85]
	s_add_u32 s16, s16, 0x200
	s_waitcnt vmcnt(4)
	v_mov_b32_e32 v80, v112
	v_mov_b32_e32 v81, v113
	v_mov_b32_e32 v82, v114
	v_mov_b32_e32 v83, v115
	v_mov_b32_e32 v84, v116
	v_mov_b32_e32 v85, v117
	v_mov_b32_e32 v86, v118
	v_mov_b32_e32 v87, v119
	s_bitcmp0_b32 s19, 3
	s_cbranch_scc1 .Lcv_skip_4
	v_lshlrev_b32_e32 v88, 16, v208
	v_and_b32_e32 v89, 0xffff0000, v208
	v_lshlrev_b32_e32 v90, 16, v209
	v_and_b32_e32 v91, 0xffff0000, v209
	v_lshlrev_b32_e32 v92, 16, v210
	v_and_b32_e32 v93, 0xffff0000, v210
	v_lshlrev_b32_e32 v94, 16, v211
	v_and_b32_e32 v95, 0xffff0000, v211
	v_fmac_f32_e32 v80, v24, v88
	v_fmac_f32_e32 v81, v25, v89
	v_fmac_f32_e32 v82, v26, v90
	v_fmac_f32_e32 v83, v27, v91
	v_fmac_f32_e32 v84, v28, v92
	v_fmac_f32_e32 v85, v29, v93
	v_fmac_f32_e32 v86, v30, v94
	v_fmac_f32_e32 v87, v31, v95
.Lcv_skip_4:
	s_bitcmp0_b32 s19, 4
	s_cbranch_scc1 .Lcv_skip_5
	v_lshlrev_b32_e32 v88, 16, v212
	v_and_b32_e32 v89, 0xffff0000, v212
	v_lshlrev_b32_e32 v90, 16, v213
	v_and_b32_e32 v91, 0xffff0000, v213
	v_lshlrev_b32_e32 v92, 16, v214
	v_and_b32_e32 v93, 0xffff0000, v214
	v_lshlrev_b32_e32 v94, 16, v215
	v_and_b32_e32 v95, 0xffff0000, v215
	v_fmac_f32_e32 v80, v32, v88
	v_fmac_f32_e32 v81, v33, v89
	v_fmac_f32_e32 v82, v34, v90
	v_fmac_f32_e32 v83, v35, v91
	v_fmac_f32_e32 v84, v36, v92
	v_fmac_f32_e32 v85, v37, v93
	v_fmac_f32_e32 v86, v38, v94
	v_fmac_f32_e32 v87, v39, v95
.Lcv_skip_5:
	s_bitcmp0_b32 s19, 5
	s_cbranch_scc1 .Lcv_skip_6
	v_lshlrev_b32_e32 v88, 16, v216
	v_and_b32_e32 v89, 0xffff0000, v216
	v_lshlrev_b32_e32 v90, 16, v217
	v_and_b32_e32 v91, 0xffff0000, v217
	v_lshlrev_b32_e32 v92, 16, v218
	v_and_b32_e32 v93, 0xffff0000, v218
	v_lshlrev_b32_e32 v94, 16, v219
	v_and_b32_e32 v95, 0xffff0000, v219
	v_fmac_f32_e32 v80, v40, v88
	v_fmac_f32_e32 v81, v41, v89
	v_fmac_f32_e32 v82, v42, v90
	v_fmac_f32_e32 v83, v43, v91
	v_fmac_f32_e32 v84, v44, v92
	v_fmac_f32_e32 v85, v45, v93
	v_fmac_f32_e32 v86, v46, v94
	v_fmac_f32_e32 v87, v47, v95
.Lcv_skip_6:
	v_mul_f32_e32 v93, 0xbfb8aa3b, v80
	v_exp_f32_e32 v93, v93
	s_nop 0
	v_add_f32_e32 v88, 1.0, v93
	v_div_scale_f32 v89, s[12:13], v88, v88, v80
	v_rcp_f32_e32 v90, v89
	s_nop 0
	v_fma_f32 v93, -v89, v90, 1.0
	v_fmac_f32_e32 v90, v93, v90
	v_div_scale_f32 v91, vcc, v80, v88, v80
	v_mul_f32_e32 v92, v91, v90
	v_fma_f32 v93, -v89, v92, v91
	v_fmac_f32_e32 v92, v93, v90
	v_fma_f32 v91, -v89, v92, v91
	v_div_fmas_f32 v91, v91, v90, v92
	v_div_fixup_f32 v91, v91, v88, v80
	v_mul_f32_e32 v99, 0xbfb8aa3b, v81
	v_exp_f32_e32 v99, v99
	s_nop 0
	v_add_f32_e32 v94, 1.0, v99
	v_div_scale_f32 v95, s[12:13], v94, v94, v81
	v_rcp_f32_e32 v96, v95
	s_nop 0
	v_fma_f32 v99, -v95, v96, 1.0
	v_fmac_f32_e32 v96, v99, v96
	v_div_scale_f32 v97, vcc, v81, v94, v81
	v_mul_f32_e32 v98, v97, v96
	v_fma_f32 v99, -v95, v98, v97
	v_fmac_f32_e32 v98, v99, v96
	v_fma_f32 v97, -v95, v98, v97
	v_div_fmas_f32 v97, v97, v96, v98
	v_div_fixup_f32 v97, v97, v94, v81
	v_cvt_pk_bf16_f32 v104, v91, v97
	v_mul_f32_e32 v93, 0xbfb8aa3b, v82
	v_exp_f32_e32 v93, v93
	s_nop 0
	v_add_f32_e32 v88, 1.0, v93
	v_div_scale_f32 v89, s[12:13], v88, v88, v82
	v_rcp_f32_e32 v90, v89
	s_nop 0
	v_fma_f32 v93, -v89, v90, 1.0
	v_fmac_f32_e32 v90, v93, v90
	v_div_scale_f32 v91, vcc, v82, v88, v82
	v_mul_f32_e32 v92, v91, v90
	v_fma_f32 v93, -v89, v92, v91
	v_fmac_f32_e32 v92, v93, v90
	v_fma_f32 v91, -v89, v92, v91
	v_div_fmas_f32 v91, v91, v90, v92
	v_div_fixup_f32 v91, v91, v88, v82
	v_mul_f32_e32 v99, 0xbfb8aa3b, v83
	v_exp_f32_e32 v99, v99
	s_nop 0
	v_add_f32_e32 v94, 1.0, v99
	v_div_scale_f32 v95, s[12:13], v94, v94, v83
	v_rcp_f32_e32 v96, v95
	s_nop 0
	v_fma_f32 v99, -v95, v96, 1.0
	v_fmac_f32_e32 v96, v99, v96
	v_div_scale_f32 v97, vcc, v83, v94, v83
	v_mul_f32_e32 v98, v97, v96
	v_fma_f32 v99, -v95, v98, v97
	v_fmac_f32_e32 v98, v99, v96
	v_fma_f32 v97, -v95, v98, v97
	v_div_fmas_f32 v97, v97, v96, v98
	v_div_fixup_f32 v97, v97, v94, v83
	v_cvt_pk_bf16_f32 v105, v91, v97
	v_mul_f32_e32 v93, 0xbfb8aa3b, v84
	v_exp_f32_e32 v93, v93
	s_nop 0
	v_add_f32_e32 v88, 1.0, v93
	v_div_scale_f32 v89, s[12:13], v88, v88, v84
	v_rcp_f32_e32 v90, v89
	s_nop 0
	v_fma_f32 v93, -v89, v90, 1.0
	v_fmac_f32_e32 v90, v93, v90
	v_div_scale_f32 v91, vcc, v84, v88, v84
	v_mul_f32_e32 v92, v91, v90
	v_fma_f32 v93, -v89, v92, v91
	v_fmac_f32_e32 v92, v93, v90
	v_fma_f32 v91, -v89, v92, v91
	v_div_fmas_f32 v91, v91, v90, v92
	v_div_fixup_f32 v91, v91, v88, v84
	v_mul_f32_e32 v99, 0xbfb8aa3b, v85
	v_exp_f32_e32 v99, v99
	s_nop 0
	v_add_f32_e32 v94, 1.0, v99
	v_div_scale_f32 v95, s[12:13], v94, v94, v85
	v_rcp_f32_e32 v96, v95
	s_nop 0
	v_fma_f32 v99, -v95, v96, 1.0
	v_fmac_f32_e32 v96, v99, v96
	v_div_scale_f32 v97, vcc, v85, v94, v85
	v_mul_f32_e32 v98, v97, v96
	v_fma_f32 v99, -v95, v98, v97
	v_fmac_f32_e32 v98, v99, v96
	v_fma_f32 v97, -v95, v98, v97
	v_div_fmas_f32 v97, v97, v96, v98
	v_div_fixup_f32 v97, v97, v94, v85
	v_cvt_pk_bf16_f32 v106, v91, v97
	v_mul_f32_e32 v93, 0xbfb8aa3b, v86
	v_exp_f32_e32 v93, v93
	s_nop 0
	v_add_f32_e32 v88, 1.0, v93
	v_div_scale_f32 v89, s[12:13], v88, v88, v86
	v_rcp_f32_e32 v90, v89
	s_nop 0
	v_fma_f32 v93, -v89, v90, 1.0
	v_fmac_f32_e32 v90, v93, v90
	v_div_scale_f32 v91, vcc, v86, v88, v86
	v_mul_f32_e32 v92, v91, v90
	v_fma_f32 v93, -v89, v92, v91
	v_fmac_f32_e32 v92, v93, v90
	v_fma_f32 v91, -v89, v92, v91
	v_div_fmas_f32 v91, v91, v90, v92
	v_div_fixup_f32 v91, v91, v88, v86
	v_mul_f32_e32 v99, 0xbfb8aa3b, v87
	v_exp_f32_e32 v99, v99
	s_nop 0
	v_add_f32_e32 v94, 1.0, v99
	v_div_scale_f32 v95, s[12:13], v94, v94, v87
	v_rcp_f32_e32 v96, v95
	s_nop 0
	v_fma_f32 v99, -v95, v96, 1.0
	v_fmac_f32_e32 v96, v99, v96
	v_div_scale_f32 v97, vcc, v87, v94, v87
	v_mul_f32_e32 v98, v97, v96
	v_fma_f32 v99, -v95, v98, v97
	v_fmac_f32_e32 v98, v99, v96
	v_fma_f32 v97, -v95, v98, v97
	v_div_fmas_f32 v97, v97, v96, v98
	v_div_fixup_f32 v97, v97, v94, v87
	v_cvt_pk_bf16_f32 v107, v91, v97
	s_lshl_b32 s22, s17, 12
	s_add_u32 s22, s4, s22
	s_addc_u32 s23, s5, 0
	s_add_u32 s17, s17, 0x200
	global_store_dwordx4 v194, v[104:107], s[22:23]
	s_and_b32 s20, s16, 0xff
	s_mov_b32 s19, 0x38
	s_cmp_eq_u32 s20, 0
	s_cselect_b32 s21, 8, 0
	s_andn2_b32 s19, s19, s21
	s_cmp_eq_u32 s20, 0xff
	s_cselect_b32 s21, 32, 0
	s_andn2_b32 s19, s19, s21
	s_mul_i32 s22, s16, 0x3000
	s_mul_hi_u32 s23, s16, 0x3000
	s_add_u32 s22, s0, s22
	s_addc_u32 s23, s1, s23
	s_sub_u32 s22, s22, 0x3000
	s_subb_u32 s23, s23, 0
	s_bitcmp1_b32 s19, 3
	s_cselect_b32 s24, 0x0, s48
	s_add_u32 s80, s22, s24
	s_addc_u32 s81, s23, 0
	global_load_dwordx4 v[208:211], v194, s[80:81]
	s_bitcmp1_b32 s19, 4
	s_cselect_b32 s24, 0x3000, s48
	s_add_u32 s82, s22, s24
	s_addc_u32 s83, s23, 0
	global_load_dwordx4 v[212:215], v194, s[82:83]
	s_bitcmp1_b32 s19, 5
	s_cselect_b32 s24, 0x6000, s48
	s_add_u32 s84, s22, s24
	s_addc_u32 s85, s23, 0
	global_load_dwordx4 v[216:219], v194, s[84:85]
	s_add_u32 s16, s16, 0x200
	s_waitcnt vmcnt(4)
	v_mov_b32_e32 v80, v112
	v_mov_b32_e32 v81, v113
	v_mov_b32_e32 v82, v114
	v_mov_b32_e32 v83, v115
	v_mov_b32_e32 v84, v116
	v_mov_b32_e32 v85, v117
	v_mov_b32_e32 v86, v118
	v_mov_b32_e32 v87, v119
	s_bitcmp0_b32 s18, 3
	s_cbranch_scc1 .Lcv_skip_7
	v_lshlrev_b32_e32 v88, 16, v196
	v_and_b32_e32 v89, 0xffff0000, v196
	v_lshlrev_b32_e32 v90, 16, v197
	v_and_b32_e32 v91, 0xffff0000, v197
	v_lshlrev_b32_e32 v92, 16, v198
	v_and_b32_e32 v93, 0xffff0000, v198
	v_lshlrev_b32_e32 v94, 16, v199
	v_and_b32_e32 v95, 0xffff0000, v199
	v_fmac_f32_e32 v80, v24, v88
	v_fmac_f32_e32 v81, v25, v89
	v_fmac_f32_e32 v82, v26, v90
	v_fmac_f32_e32 v83, v27, v91
	v_fmac_f32_e32 v84, v28, v92
	v_fmac_f32_e32 v85, v29, v93
	v_fmac_f32_e32 v86, v30, v94
	v_fmac_f32_e32 v87, v31, v95

.Lcv_skip_21:
	v_mul_f32_e32 v93, 0xbfb8aa3b, v80
	v_exp_f32_e32 v93, v93
	s_nop 0
	v_add_f32_e32 v88, 1.0, v93
	v_div_scale_f32 v89, s[12:13], v88, v88, v80
	v_rcp_f32_e32 v90, v89
	s_nop 0
	v_fma_f32 v93, -v89, v90, 1.0
	v_fmac_f32_e32 v90, v93, v90
	v_div_scale_f32 v91, vcc, v80, v88, v80
	v_mul_f32_e32 v92, v91, v90
	v_fma_f32 v93, -v89, v92, v91
	v_fmac_f32_e32 v92, v93, v90
	v_fma_f32 v91, -v89, v92, v91
	v_div_fmas_f32 v91, v91, v90, v92
	v_div_fixup_f32 v91, v91, v88, v80
	v_mul_f32_e32 v99, 0xbfb8aa3b, v81
	v_exp_f32_e32 v99, v99
	s_nop 0
	v_add_f32_e32 v94, 1.0, v99
	v_div_scale_f32 v95, s[12:13], v94, v94, v81
	v_rcp_f32_e32 v96, v95
	s_nop 0
	v_fma_f32 v99, -v95, v96, 1.0
	v_fmac_f32_e32 v96, v99, v96
	v_div_scale_f32 v97, vcc, v81, v94, v81
	v_mul_f32_e32 v98, v97, v96
	v_fma_f32 v99, -v95, v98, v97
	v_fmac_f32_e32 v98, v99, v96
	v_fma_f32 v97, -v95, v98, v97
	v_div_fmas_f32 v97, v97, v96, v98
	v_div_fixup_f32 v97, v97, v94, v81
	v_cvt_pk_bf16_f32 v104, v91, v97
	v_mul_f32_e32 v93, 0xbfb8aa3b, v82
	v_exp_f32_e32 v93, v93
	s_nop 0
	v_add_f32_e32 v88, 1.0, v93
	v_div_scale_f32 v89, s[12:13], v88, v88, v82
	v_rcp_f32_e32 v90, v89
	s_nop 0
	v_fma_f32 v93, -v89, v90, 1.0
	v_fmac_f32_e32 v90, v93, v90
	v_div_scale_f32 v91, vcc, v82, v88, v82
	v_mul_f32_e32 v92, v91, v90
	v_fma_f32 v93, -v89, v92, v91
	v_fmac_f32_e32 v92, v93, v90
	v_fma_f32 v91, -v89, v92, v91
	v_div_fmas_f32 v91, v91, v90, v92
	v_div_fixup_f32 v91, v91, v88, v82
	v_mul_f32_e32 v99, 0xbfb8aa3b, v83
	v_exp_f32_e32 v99, v99
	s_nop 0
	v_add_f32_e32 v94, 1.0, v99
	v_div_scale_f32 v95, s[12:13], v94, v94, v83
	v_rcp_f32_e32 v96, v95
	s_nop 0
	v_fma_f32 v99, -v95, v96, 1.0
	v_fmac_f32_e32 v96, v99, v96
	v_div_scale_f32 v97, vcc, v83, v94, v83
	v_mul_f32_e32 v98, v97, v96
	v_fma_f32 v99, -v95, v98, v97
	v_fmac_f32_e32 v98, v99, v96
	v_fma_f32 v97, -v95, v98, v97
	v_div_fmas_f32 v97, v97, v96, v98
	v_div_fixup_f32 v97, v97, v94, v83
	v_cvt_pk_bf16_f32 v105, v91, v97
	v_mul_f32_e32 v93, 0xbfb8aa3b, v84
	v_exp_f32_e32 v93, v93
	s_nop 0
	v_add_f32_e32 v88, 1.0, v93
	v_div_scale_f32 v89, s[12:13], v88, v88, v84
	v_rcp_f32_e32 v90, v89
	s_nop 0
	v_fma_f32 v93, -v89, v90, 1.0
	v_fmac_f32_e32 v90, v93, v90
	v_div_scale_f32 v91, vcc, v84, v88, v84
	v_mul_f32_e32 v92, v91, v90
	v_fma_f32 v93, -v89, v92, v91
	v_fmac_f32_e32 v92, v93, v90
	v_fma_f32 v91, -v89, v92, v91
	v_div_fmas_f32 v91, v91, v90, v92
	v_div_fixup_f32 v91, v91, v88, v84
	v_mul_f32_e32 v99, 0xbfb8aa3b, v85
	v_exp_f32_e32 v99, v99
	s_nop 0
	v_add_f32_e32 v94, 1.0, v99
	v_div_scale_f32 v95, s[12:13], v94, v94, v85
	v_rcp_f32_e32 v96, v95
	s_nop 0
	v_fma_f32 v99, -v95, v96, 1.0
	v_fmac_f32_e32 v96, v99, v96
	v_div_scale_f32 v97, vcc, v85, v94, v85
	v_mul_f32_e32 v98, v97, v96
	v_fma_f32 v99, -v95, v98, v97
	v_fmac_f32_e32 v98, v99, v96
	v_fma_f32 v97, -v95, v98, v97
	v_div_fmas_f32 v97, v97, v96, v98
	v_div_fixup_f32 v97, v97, v94, v85
	v_cvt_pk_bf16_f32 v106, v91, v97
	v_mul_f32_e32 v93, 0xbfb8aa3b, v86
	v_exp_f32_e32 v93, v93
	s_nop 0
	v_add_f32_e32 v88, 1.0, v93
	v_div_scale_f32 v89, s[12:13], v88, v88, v86
	v_rcp_f32_e32 v90, v89
	s_nop 0
	v_fma_f32 v93, -v89, v90, 1.0
	v_fmac_f32_e32 v90, v93, v90
	v_div_scale_f32 v91, vcc, v86, v88, v86
	v_mul_f32_e32 v92, v91, v90
	v_fma_f32 v93, -v89, v92, v91
	v_fmac_f32_e32 v92, v93, v90
	v_fma_f32 v91, -v89, v92, v91
	v_div_fmas_f32 v91, v91, v90, v92
	v_div_fixup_f32 v91, v91, v88, v86
	v_mul_f32_e32 v99, 0xbfb8aa3b, v87
	v_exp_f32_e32 v99, v99
	s_nop 0
	v_add_f32_e32 v94, 1.0, v99
	v_div_scale_f32 v95, s[12:13], v94, v94, v87
	v_rcp_f32_e32 v96, v95
	s_nop 0
	v_fma_f32 v99, -v95, v96, 1.0
	v_fmac_f32_e32 v96, v99, v96
	v_div_scale_f32 v97, vcc, v87, v94, v87
	v_mul_f32_e32 v98, v97, v96
	v_fma_f32 v99, -v95, v98, v97
	v_fmac_f32_e32 v98, v99, v96
	v_fma_f32 v97, -v95, v98, v97
	v_div_fmas_f32 v97, v97, v96, v98
	v_div_fixup_f32 v97, v97, v94, v87
	v_cvt_pk_bf16_f32 v107, v91, v97
	s_lshl_b32 s22, s17, 12
	s_add_u32 s22, s4, s22
	s_addc_u32 s23, s5, 0
	s_add_u32 s17, s17, 0x200
	global_store_dwordx4 v194, v[104:107], s[22:23]
	s_and_b32 s20, s16, 63
	s_bfe_u32 s26, s16, 0x50006
	s_mov_b32 s18, 0x1ff
	s_cmp_eq_u32 s20, 0
	s_cselect_b32 s21, 0x49, 0
	s_andn2_b32 s18, s18, s21
	s_cmp_eq_u32 s20, 63
	s_cselect_b32 s21, 0x124, 0
	s_andn2_b32 s18, s18, s21
	s_cmp_eq_u32 s26, 0
	s_cselect_b32 s21, 0x7, 0
	s_andn2_b32 s18, s18, s21
	s_cmp_eq_u32 s26, 31
	s_cselect_b32 s21, 0x1c0, 0
	s_andn2_b32 s18, s18, s21
	s_mul_i32 s22, s16, 0x3000
	s_mul_hi_u32 s23, s16, 0x3000
	s_add_u32 s22, s0, s22
	s_addc_u32 s23, s1, s23
	s_sub_u32 s22, s22, 0xc3000
	s_subb_u32 s23, s23, 0
	s_bitcmp1_b32 s18, 0
	s_cselect_b32 s24, 0x0, s27
	s_add_u32 s74, s22, s24
	s_addc_u32 s75, s23, 0
	global_load_dwordx4 v[120:123], v194, s[74:75]
	s_bitcmp1_b32 s18, 1
	s_cselect_b32 s24, 0x3000, s27
	s_add_u32 s76, s22, s24
	s_addc_u32 s77, s23, 0
	global_load_dwordx4 v[124:127], v194, s[76:77]
	s_bitcmp1_b32 s18, 2
	s_cselect_b32 s24, 0x6000, s27
	s_add_u32 s78, s22, s24
	s_addc_u32 s79, s23, 0
	global_load_dwordx4 v[128:131], v194, s[78:79]
	s_bitcmp1_b32 s18, 3
	s_cselect_b32 s24, 0xc0000, s27
	s_add_u32 s80, s22, s24
	s_addc_u32 s81, s23, 0
	global_load_dwordx4 v[132:135], v194, s[80:81]
	s_bitcmp1_b32 s18, 4
	s_cselect_b32 s24, 0xc3000, s27
	s_add_u32 s82, s22, s24
	s_addc_u32 s83, s23, 0
	global_load_dwordx4 v[136:139], v194, s[82:83]
	s_bitcmp1_b32 s18, 5
	s_cselect_b32 s24, 0xc6000, s27
	s_add_u32 s84, s22, s24
	s_addc_u32 s85, s23, 0
	global_load_dwordx4 v[140:143], v194, s[84:85]
	s_bitcmp1_b32 s18, 6
	s_cselect_b32 s24, 0x180000, s27
	s_add_u32 s86, s22, s24
	s_addc_u32 s87, s23, 0
	global_load_dwordx4 v[144:147], v194, s[86:87]
	s_bitcmp1_b32 s18, 7
	s_cselect_b32 s24, 0x183000, s27
	s_add_u32 s88, s22, s24
	s_addc_u32 s89, s23, 0
	global_load_dwordx4 v[148:151], v194, s[88:89]
	s_bitcmp1_b32 s18, 8
	s_cselect_b32 s24, 0x186000, s27
	s_add_u32 s90, s22, s24
	s_addc_u32 s91, s23, 0
	global_load_dwordx4 v[152:155], v194, s[90:91]
	s_add_u32 s16, s16, 0x200
	s_waitcnt vmcnt(10)
	v_mov_b32_e32 v80, v112
	v_mov_b32_e32 v81, v113
	v_mov_b32_e32 v82, v114
	v_mov_b32_e32 v83, v115
	v_mov_b32_e32 v84, v116
	v_mov_b32_e32 v85, v117
	v_mov_b32_e32 v86, v118
	v_mov_b32_e32 v87, v119
	s_bitcmp0_b32 s19, 3
	s_cbranch_scc1 .Lcv_skip_22
	v_lshlrev_b32_e32 v88, 16, v208
	v_and_b32_e32 v89, 0xffff0000, v208
	v_lshlrev_b32_e32 v90, 16, v209
	v_and_b32_e32 v91, 0xffff0000, v209
	v_lshlrev_b32_e32 v92, 16, v210
	v_and_b32_e32 v93, 0xffff0000, v210
	v_lshlrev_b32_e32 v94, 16, v211
	v_and_b32_e32 v95, 0xffff0000, v211
	v_fmac_f32_e32 v80, v24, v88
	v_fmac_f32_e32 v81, v25, v89
	v_fmac_f32_e32 v82, v26, v90
	v_fmac_f32_e32 v83, v27, v91
	v_fmac_f32_e32 v84, v28, v92
	v_fmac_f32_e32 v85, v29, v93
	v_fmac_f32_e32 v86, v30, v94
	v_fmac_f32_e32 v87, v31, v95

.Lcv_skip_24:
	v_mul_f32_e32 v93, 0xbfb8aa3b, v80
	v_exp_f32_e32 v93, v93
	s_nop 0
	v_add_f32_e32 v88, 1.0, v93
	v_div_scale_f32 v89, s[12:13], v88, v88, v80
	v_rcp_f32_e32 v90, v89
	s_nop 0
	v_fma_f32 v93, -v89, v90, 1.0
	v_fmac_f32_e32 v90, v93, v90
	v_div_scale_f32 v91, vcc, v80, v88, v80
	v_mul_f32_e32 v92, v91, v90
	v_fma_f32 v93, -v89, v92, v91
	v_fmac_f32_e32 v92, v93, v90
	v_fma_f32 v91, -v89, v92, v91
	v_div_fmas_f32 v91, v91, v90, v92
	v_div_fixup_f32 v91, v91, v88, v80
	v_mul_f32_e32 v99, 0xbfb8aa3b, v81
	v_exp_f32_e32 v99, v99
	s_nop 0
	v_add_f32_e32 v94, 1.0, v99
	v_div_scale_f32 v95, s[12:13], v94, v94, v81
	v_rcp_f32_e32 v96, v95
	s_nop 0
	v_fma_f32 v99, -v95, v96, 1.0
	v_fmac_f32_e32 v96, v99, v96
	v_div_scale_f32 v97, vcc, v81, v94, v81
	v_mul_f32_e32 v98, v97, v96
	v_fma_f32 v99, -v95, v98, v97
	v_fmac_f32_e32 v98, v99, v96
	v_fma_f32 v97, -v95, v98, v97
	v_div_fmas_f32 v97, v97, v96, v98
	v_div_fixup_f32 v97, v97, v94, v81
	v_cvt_pk_bf16_f32 v104, v91, v97
	v_mul_f32_e32 v93, 0xbfb8aa3b, v82
	v_exp_f32_e32 v93, v93
	s_nop 0
	v_add_f32_e32 v88, 1.0, v93
	v_div_scale_f32 v89, s[12:13], v88, v88, v82
	v_rcp_f32_e32 v90, v89
	s_nop 0
	v_fma_f32 v93, -v89, v90, 1.0
	v_fmac_f32_e32 v90, v93, v90
	v_div_scale_f32 v91, vcc, v82, v88, v82
	v_mul_f32_e32 v92, v91, v90
	v_fma_f32 v93, -v89, v92, v91
	v_fmac_f32_e32 v92, v93, v90
	v_fma_f32 v91, -v89, v92, v91
	v_div_fmas_f32 v91, v91, v90, v92
	v_div_fixup_f32 v91, v91, v88, v82
	v_mul_f32_e32 v99, 0xbfb8aa3b, v83
	v_exp_f32_e32 v99, v99
	s_nop 0
	v_add_f32_e32 v94, 1.0, v99
	v_div_scale_f32 v95, s[12:13], v94, v94, v83
	v_rcp_f32_e32 v96, v95
	s_nop 0
	v_fma_f32 v99, -v95, v96, 1.0
	v_fmac_f32_e32 v96, v99, v96
	v_div_scale_f32 v97, vcc, v83, v94, v83
	v_mul_f32_e32 v98, v97, v96
	v_fma_f32 v99, -v95, v98, v97
	v_fmac_f32_e32 v98, v99, v96
	v_fma_f32 v97, -v95, v98, v97
	v_div_fmas_f32 v97, v97, v96, v98
	v_div_fixup_f32 v97, v97, v94, v83
	v_cvt_pk_bf16_f32 v105, v91, v97
	v_mul_f32_e32 v93, 0xbfb8aa3b, v84
	v_exp_f32_e32 v93, v93
	s_nop 0
	v_add_f32_e32 v88, 1.0, v93
	v_div_scale_f32 v89, s[12:13], v88, v88, v84
	v_rcp_f32_e32 v90, v89
	s_nop 0
	v_fma_f32 v93, -v89, v90, 1.0
	v_fmac_f32_e32 v90, v93, v90
	v_div_scale_f32 v91, vcc, v84, v88, v84
	v_mul_f32_e32 v92, v91, v90
	v_fma_f32 v93, -v89, v92, v91
	v_fmac_f32_e32 v92, v93, v90
	v_fma_f32 v91, -v89, v92, v91
	v_div_fmas_f32 v91, v91, v90, v92
	v_div_fixup_f32 v91, v91, v88, v84
	v_mul_f32_e32 v99, 0xbfb8aa3b, v85
	v_exp_f32_e32 v99, v99
	s_nop 0
	v_add_f32_e32 v94, 1.0, v99
	v_div_scale_f32 v95, s[12:13], v94, v94, v85
	v_rcp_f32_e32 v96, v95
	s_nop 0
	v_fma_f32 v99, -v95, v96, 1.0
	v_fmac_f32_e32 v96, v99, v96
	v_div_scale_f32 v97, vcc, v85, v94, v85
	v_mul_f32_e32 v98, v97, v96
	v_fma_f32 v99, -v95, v98, v97
	v_fmac_f32_e32 v98, v99, v96
	v_fma_f32 v97, -v95, v98, v97
	v_div_fmas_f32 v97, v97, v96, v98
	v_div_fixup_f32 v97, v97, v94, v85
	v_cvt_pk_bf16_f32 v106, v91, v97
	v_mul_f32_e32 v93, 0xbfb8aa3b, v86
	v_exp_f32_e32 v93, v93
	s_nop 0
	v_add_f32_e32 v88, 1.0, v93
	v_div_scale_f32 v89, s[12:13], v88, v88, v86
	v_rcp_f32_e32 v90, v89
	s_nop 0
	v_fma_f32 v93, -v89, v90, 1.0
	v_fmac_f32_e32 v90, v93, v90
	v_div_scale_f32 v91, vcc, v86, v88, v86
	v_mul_f32_e32 v92, v91, v90
	v_fma_f32 v93, -v89, v92, v91
	v_fmac_f32_e32 v92, v93, v90
	v_fma_f32 v91, -v89, v92, v91
	v_div_fmas_f32 v91, v91, v90, v92
	v_div_fixup_f32 v91, v91, v88, v86
	v_mul_f32_e32 v99, 0xbfb8aa3b, v87
	v_exp_f32_e32 v99, v99
	s_nop 0
	v_add_f32_e32 v94, 1.0, v99
	v_div_scale_f32 v95, s[12:13], v94, v94, v87
	v_rcp_f32_e32 v96, v95
	s_nop 0
	v_fma_f32 v99, -v95, v96, 1.0
	v_fmac_f32_e32 v96, v99, v96
	v_div_scale_f32 v97, vcc, v87, v94, v87
	v_mul_f32_e32 v98, v97, v96
	v_fma_f32 v99, -v95, v98, v97
	v_fmac_f32_e32 v98, v99, v96
	v_fma_f32 v97, -v95, v98, v97
	v_div_fmas_f32 v97, v97, v96, v98
	v_div_fixup_f32 v97, v97, v94, v87
	v_cvt_pk_bf16_f32 v107, v91, v97
	s_lshl_b32 s22, s17, 12
	s_add_u32 s22, s4, s22
	s_addc_u32 s23, s5, 0
	s_add_u32 s17, s17, 0x200
	global_store_dwordx4 v194, v[104:107], s[22:23]
	s_and_b32 s20, s16, 63
	s_bfe_u32 s26, s16, 0x50006
	s_mov_b32 s19, 0x1ff
	s_cmp_eq_u32 s20, 0
	s_cselect_b32 s21, 0x49, 0
	s_andn2_b32 s19, s19, s21
	s_cmp_eq_u32 s20, 63
	s_cselect_b32 s21, 0x124, 0
	s_andn2_b32 s19, s19, s21
	s_cmp_eq_u32 s26, 0
	s_cselect_b32 s21, 0x7, 0
	s_andn2_b32 s19, s19, s21
	s_cmp_eq_u32 s26, 31
	s_cselect_b32 s21, 0x1c0, 0
	s_andn2_b32 s19, s19, s21
	s_mul_i32 s22, s16, 0x3000
	s_mul_hi_u32 s23, s16, 0x3000
	s_add_u32 s22, s0, s22
	s_addc_u32 s23, s1, s23
	s_sub_u32 s22, s22, 0xc3000
	s_subb_u32 s23, s23, 0
	s_bitcmp1_b32 s19, 0
	s_cselect_b32 s24, 0x0, s27
	s_add_u32 s74, s22, s24
	s_addc_u32 s75, s23, 0
	global_load_dwordx4 v[156:159], v194, s[74:75]
	s_bitcmp1_b32 s19, 1
	s_cselect_b32 s24, 0x3000, s27
	s_add_u32 s76, s22, s24
	s_addc_u32 s77, s23, 0
	global_load_dwordx4 v[160:163], v194, s[76:77]
	s_bitcmp1_b32 s19, 2
	s_cselect_b32 s24, 0x6000, s27
	s_add_u32 s78, s22, s24
	s_addc_u32 s79, s23, 0
	global_load_dwordx4 v[164:167], v194, s[78:79]
	s_bitcmp1_b32 s19, 3
	s_cselect_b32 s24, 0xc0000, s27
	s_add_u32 s80, s22, s24
	s_addc_u32 s81, s23, 0
	global_load_dwordx4 v[168:171], v194, s[80:81]
	s_bitcmp1_b32 s19, 4
	s_cselect_b32 s24, 0xc3000, s27
	s_add_u32 s82, s22, s24
	s_addc_u32 s83, s23, 0
	global_load_dwordx4 v[172:175], v194, s[82:83]
	s_bitcmp1_b32 s19, 5
	s_cselect_b32 s24, 0xc6000, s27
	s_add_u32 s84, s22, s24
	s_addc_u32 s85, s23, 0
	global_load_dwordx4 v[176:179], v194, s[84:85]
	s_bitcmp1_b32 s19, 6
	s_cselect_b32 s24, 0x180000, s27
	s_add_u32 s86, s22, s24
	s_addc_u32 s87, s23, 0
	global_load_dwordx4 v[180:183], v194, s[86:87]
	s_bitcmp1_b32 s19, 7
	s_cselect_b32 s24, 0x183000, s27
	s_add_u32 s88, s22, s24
	s_addc_u32 s89, s23, 0
	global_load_dwordx4 v[186:189], v194, s[88:89]
	s_bitcmp1_b32 s19, 8
	s_cselect_b32 s24, 0x186000, s27
	s_add_u32 s90, s22, s24
	s_addc_u32 s91, s23, 0
	global_load_dwordx4 v[190:193], v194, s[90:91]
	s_add_u32 s16, s16, 0x200
	s_waitcnt vmcnt(10)
	v_mov_b32_e32 v80, v112
	v_mov_b32_e32 v81, v113
	v_mov_b32_e32 v82, v114
	v_mov_b32_e32 v83, v115
	v_mov_b32_e32 v84, v116
	v_mov_b32_e32 v85, v117
	v_mov_b32_e32 v86, v118
	v_mov_b32_e32 v87, v119
	s_bitcmp0_b32 s18, 0
	s_cbranch_scc1 .Lcv_skip_25
	v_lshlrev_b32_e32 v88, 16, v120
	v_and_b32_e32 v89, 0xffff0000, v120
	v_lshlrev_b32_e32 v90, 16, v121
	v_and_b32_e32 v91, 0xffff0000, v121
	v_lshlrev_b32_e32 v92, 16, v122
	v_and_b32_e32 v93, 0xffff0000, v122
	v_lshlrev_b32_e32 v94, 16, v123
	v_and_b32_e32 v95, 0xffff0000, v123
	v_fmac_f32_e32 v80, v0, v88
	v_fmac_f32_e32 v81, v1, v89
	v_fmac_f32_e32 v82, v2, v90
	v_fmac_f32_e32 v83, v3, v91
	v_fmac_f32_e32 v84, v4, v92
	v_fmac_f32_e32 v85, v5, v93
	v_fmac_f32_e32 v86, v6, v94
	v_fmac_f32_e32 v87, v7, v95
.Lcv_skip_25:
	s_bitcmp0_b32 s18, 1
	s_cbranch_scc1 .Lcv_skip_26
	v_lshlrev_b32_e32 v88, 16, v124
	v_and_b32_e32 v89, 0xffff0000, v124
	v_lshlrev_b32_e32 v90, 16, v125
	v_and_b32_e32 v91, 0xffff0000, v125
	v_lshlrev_b32_e32 v92, 16, v126
	v_and_b32_e32 v93, 0xffff0000, v126
	v_lshlrev_b32_e32 v94, 16, v127
	v_and_b32_e32 v95, 0xffff0000, v127
	v_fmac_f32_e32 v80, v8, v88
	v_fmac_f32_e32 v81, v9, v89
	v_fmac_f32_e32 v82, v10, v90
	v_fmac_f32_e32 v83, v11, v91
	v_fmac_f32_e32 v84, v12, v92
	v_fmac_f32_e32 v85, v13, v93
	v_fmac_f32_e32 v86, v14, v94
	v_fmac_f32_e32 v87, v15, v95
.Lcv_skip_26:
	s_bitcmp0_b32 s18, 2
	s_cbranch_scc1 .Lcv_skip_27
	v_lshlrev_b32_e32 v88, 16, v128
	v_and_b32_e32 v89, 0xffff0000, v128
	v_lshlrev_b32_e32 v90, 16, v129
	v_and_b32_e32 v91, 0xffff0000, v129
	v_lshlrev_b32_e32 v92, 16, v130
	v_and_b32_e32 v93, 0xffff0000, v130
	v_lshlrev_b32_e32 v94, 16, v131
	v_and_b32_e32 v95, 0xffff0000, v131
	v_fmac_f32_e32 v80, v16, v88
	v_fmac_f32_e32 v81, v17, v89
	v_fmac_f32_e32 v82, v18, v90
	v_fmac_f32_e32 v83, v19, v91
	v_fmac_f32_e32 v84, v20, v92
	v_fmac_f32_e32 v85, v21, v93
	v_fmac_f32_e32 v86, v22, v94
	v_fmac_f32_e32 v87, v23, v95
.Lcv_skip_27:
	s_bitcmp0_b32 s18, 3
	s_cbranch_scc1 .Lcv_skip_28
	v_lshlrev_b32_e32 v88, 16, v132
	v_and_b32_e32 v89, 0xffff0000, v132
	v_lshlrev_b32_e32 v90, 16, v133
	v_and_b32_e32 v91, 0xffff0000, v133
	v_lshlrev_b32_e32 v92, 16, v134
	v_and_b32_e32 v93, 0xffff0000, v134
	v_lshlrev_b32_e32 v94, 16, v135
	v_and_b32_e32 v95, 0xffff0000, v135
	v_fmac_f32_e32 v80, v24, v88
	v_fmac_f32_e32 v81, v25, v89
	v_fmac_f32_e32 v82, v26, v90
	v_fmac_f32_e32 v83, v27, v91
	v_fmac_f32_e32 v84, v28, v92
	v_fmac_f32_e32 v85, v29, v93
	v_fmac_f32_e32 v86, v30, v94
	v_fmac_f32_e32 v87, v31, v95
.Lcv_skip_28:
	s_bitcmp0_b32 s18, 4
	s_cbranch_scc1 .Lcv_skip_29
	v_lshlrev_b32_e32 v88, 16, v136
	v_and_b32_e32 v89, 0xffff0000, v136
	v_lshlrev_b32_e32 v90, 16, v137
	v_and_b32_e32 v91, 0xffff0000, v137
	v_lshlrev_b32_e32 v92, 16, v138
	v_and_b32_e32 v93, 0xffff0000, v138
	v_lshlrev_b32_e32 v94, 16, v139
	v_and_b32_e32 v95, 0xffff0000, v139
	v_fmac_f32_e32 v80, v32, v88
	v_fmac_f32_e32 v81, v33, v89
	v_fmac_f32_e32 v82, v34, v90
	v_fmac_f32_e32 v83, v35, v91
	v_fmac_f32_e32 v84, v36, v92
	v_fmac_f32_e32 v85, v37, v93
	v_fmac_f32_e32 v86, v38, v94
	v_fmac_f32_e32 v87, v39, v95
.Lcv_skip_29:
	s_bitcmp0_b32 s18, 5
	s_cbranch_scc1 .Lcv_skip_30
	v_lshlrev_b32_e32 v88, 16, v140
	v_and_b32_e32 v89, 0xffff0000, v140
	v_lshlrev_b32_e32 v90, 16, v141
	v_and_b32_e32 v91, 0xffff0000, v141
	v_lshlrev_b32_e32 v92, 16, v142
	v_and_b32_e32 v93, 0xffff0000, v142
	v_lshlrev_b32_e32 v94, 16, v143
	v_and_b32_e32 v95, 0xffff0000, v143
	v_fmac_f32_e32 v80, v40, v88
	v_fmac_f32_e32 v81, v41, v89
	v_fmac_f32_e32 v82, v42, v90
	v_fmac_f32_e32 v83, v43, v91
	v_fmac_f32_e32 v84, v44, v92
	v_fmac_f32_e32 v85, v45, v93
	v_fmac_f32_e32 v86, v46, v94
	v_fmac_f32_e32 v87, v47, v95
.Lcv_skip_30:
	s_bitcmp0_b32 s18, 6
	s_cbranch_scc1 .Lcv_skip_31
	v_lshlrev_b32_e32 v88, 16, v144
	v_and_b32_e32 v89, 0xffff0000, v144
	v_lshlrev_b32_e32 v90, 16, v145
	v_and_b32_e32 v91, 0xffff0000, v145
	v_lshlrev_b32_e32 v92, 16, v146
	v_and_b32_e32 v93, 0xffff0000, v146
	v_lshlrev_b32_e32 v94, 16, v147
	v_and_b32_e32 v95, 0xffff0000, v147
	v_fmac_f32_e32 v80, v48, v88
	v_fmac_f32_e32 v81, v49, v89
	v_fmac_f32_e32 v82, v50, v90
	v_fmac_f32_e32 v83, v51, v91
	v_fmac_f32_e32 v84, v52, v92
	v_fmac_f32_e32 v85, v53, v93
	v_fmac_f32_e32 v86, v54, v94
	v_fmac_f32_e32 v87, v55, v95
.Lcv_skip_31:
	s_bitcmp0_b32 s18, 7
	s_cbranch_scc1 .Lcv_skip_32
	v_lshlrev_b32_e32 v88, 16, v148
	v_and_b32_e32 v89, 0xffff0000, v148
	v_lshlrev_b32_e32 v90, 16, v149
	v_and_b32_e32 v91, 0xffff0000, v149
	v_lshlrev_b32_e32 v92, 16, v150
	v_and_b32_e32 v93, 0xffff0000, v150
	v_lshlrev_b32_e32 v94, 16, v151
	v_and_b32_e32 v95, 0xffff0000, v151
	v_fmac_f32_e32 v80, v56, v88
	v_fmac_f32_e32 v81, v57, v89
	v_fmac_f32_e32 v82, v58, v90
	v_fmac_f32_e32 v83, v59, v91
	v_fmac_f32_e32 v84, v60, v92
	v_fmac_f32_e32 v85, v61, v93
	v_fmac_f32_e32 v86, v62, v94
	v_fmac_f32_e32 v87, v63, v95
.Lcv_skip_32:
	s_bitcmp0_b32 s18, 8
	s_cbranch_scc1 .Lcv_skip_33
	v_lshlrev_b32_e32 v88, 16, v152
	v_and_b32_e32 v89, 0xffff0000, v152
	v_lshlrev_b32_e32 v90, 16, v153
	v_and_b32_e32 v91, 0xffff0000, v153
	v_lshlrev_b32_e32 v92, 16, v154
	v_and_b32_e32 v93, 0xffff0000, v154
	v_lshlrev_b32_e32 v94, 16, v155
	v_and_b32_e32 v95, 0xffff0000, v155
	v_fmac_f32_e32 v80, v64, v88
	v_fmac_f32_e32 v81, v65, v89
	v_fmac_f32_e32 v82, v66, v90
	v_fmac_f32_e32 v83, v67, v91
	v_fmac_f32_e32 v84, v68, v92
	v_fmac_f32_e32 v85, v69, v93
	v_fmac_f32_e32 v86, v70, v94
	v_fmac_f32_e32 v87, v71, v95
.Lcv_skip_33:
	v_mul_f32_e32 v93, 0xbfb8aa3b, v80
	v_exp_f32_e32 v93, v93
	s_nop 0
	v_add_f32_e32 v88, 1.0, v93
	v_div_scale_f32 v89, s[12:13], v88, v88, v80
	v_rcp_f32_e32 v90, v89
	s_nop 0
	v_fma_f32 v93, -v89, v90, 1.0
	v_fmac_f32_e32 v90, v93, v90
	v_div_scale_f32 v91, vcc, v80, v88, v80
	v_mul_f32_e32 v92, v91, v90
	v_fma_f32 v93, -v89, v92, v91
	v_fmac_f32_e32 v92, v93, v90
	v_fma_f32 v91, -v89, v92, v91
	v_div_fmas_f32 v91, v91, v90, v92
	v_div_fixup_f32 v91, v91, v88, v80
	v_mul_f32_e32 v99, 0xbfb8aa3b, v81
	v_exp_f32_e32 v99, v99
	s_nop 0
	v_add_f32_e32 v94, 1.0, v99
	v_div_scale_f32 v95, s[12:13], v94, v94, v81
	v_rcp_f32_e32 v96, v95
	s_nop 0
	v_fma_f32 v99, -v95, v96, 1.0
	v_fmac_f32_e32 v96, v99, v96
	v_div_scale_f32 v97, vcc, v81, v94, v81
	v_mul_f32_e32 v98, v97, v96
	v_fma_f32 v99, -v95, v98, v97
	v_fmac_f32_e32 v98, v99, v96
	v_fma_f32 v97, -v95, v98, v97
	v_div_fmas_f32 v97, v97, v96, v98
	v_div_fixup_f32 v97, v97, v94, v81
	v_cvt_pk_bf16_f32 v104, v91, v97
	v_mul_f32_e32 v93, 0xbfb8aa3b, v82
	v_exp_f32_e32 v93, v93
	s_nop 0
	v_add_f32_e32 v88, 1.0, v93
	v_div_scale_f32 v89, s[12:13], v88, v88, v82
	v_rcp_f32_e32 v90, v89
	s_nop 0
	v_fma_f32 v93, -v89, v90, 1.0
	v_fmac_f32_e32 v90, v93, v90
	v_div_scale_f32 v91, vcc, v82, v88, v82
	v_mul_f32_e32 v92, v91, v90
	v_fma_f32 v93, -v89, v92, v91
	v_fmac_f32_e32 v92, v93, v90
	v_fma_f32 v91, -v89, v92, v91
	v_div_fmas_f32 v91, v91, v90, v92
	v_div_fixup_f32 v91, v91, v88, v82
	v_mul_f32_e32 v99, 0xbfb8aa3b, v83
	v_exp_f32_e32 v99, v99
	s_nop 0
	v_add_f32_e32 v94, 1.0, v99
	v_div_scale_f32 v95, s[12:13], v94, v94, v83
	v_rcp_f32_e32 v96, v95
	s_nop 0
	v_fma_f32 v99, -v95, v96, 1.0
	v_fmac_f32_e32 v96, v99, v96
	v_div_scale_f32 v97, vcc, v83, v94, v83
	v_mul_f32_e32 v98, v97, v96
	v_fma_f32 v99, -v95, v98, v97
	v_fmac_f32_e32 v98, v99, v96
	v_fma_f32 v97, -v95, v98, v97
	v_div_fmas_f32 v97, v97, v96, v98
	v_div_fixup_f32 v97, v97, v94, v83
	v_cvt_pk_bf16_f32 v105, v91, v97
	v_mul_f32_e32 v93, 0xbfb8aa3b, v84
	v_exp_f32_e32 v93, v93
	s_nop 0
	v_add_f32_e32 v88, 1.0, v93
	v_div_scale_f32 v89, s[12:13], v88, v88, v84
	v_rcp_f32_e32 v90, v89
	s_nop 0
	v_fma_f32 v93, -v89, v90, 1.0
	v_fmac_f32_e32 v90, v93, v90
	v_div_scale_f32 v91, vcc, v84, v88, v84
	v_mul_f32_e32 v92, v91, v90
	v_fma_f32 v93, -v89, v92, v91
	v_fmac_f32_e32 v92, v93, v90
	v_fma_f32 v91, -v89, v92, v91
	v_div_fmas_f32 v91, v91, v90, v92
	v_div_fixup_f32 v91, v91, v88, v84
	v_mul_f32_e32 v99, 0xbfb8aa3b, v85
	v_exp_f32_e32 v99, v99
	s_nop 0
	v_add_f32_e32 v94, 1.0, v99
	v_div_scale_f32 v95, s[12:13], v94, v94, v85
	v_rcp_f32_e32 v96, v95
	s_nop 0
	v_fma_f32 v99, -v95, v96, 1.0
	v_fmac_f32_e32 v96, v99, v96
	v_div_scale_f32 v97, vcc, v85, v94, v85
	v_mul_f32_e32 v98, v97, v96
	v_fma_f32 v99, -v95, v98, v97
	v_fmac_f32_e32 v98, v99, v96
	v_fma_f32 v97, -v95, v98, v97
	v_div_fmas_f32 v97, v97, v96, v98
	v_div_fixup_f32 v97, v97, v94, v85
	v_cvt_pk_bf16_f32 v106, v91, v97
	v_mul_f32_e32 v93, 0xbfb8aa3b, v86
	v_exp_f32_e32 v93, v93
	s_nop 0
	v_add_f32_e32 v88, 1.0, v93
	v_div_scale_f32 v89, s[12:13], v88, v88, v86
	v_rcp_f32_e32 v90, v89
	s_nop 0
	v_fma_f32 v93, -v89, v90, 1.0
	v_fmac_f32_e32 v90, v93, v90
	v_div_scale_f32 v91, vcc, v86, v88, v86
	v_mul_f32_e32 v92, v91, v90
	v_fma_f32 v93, -v89, v92, v91
	v_fmac_f32_e32 v92, v93, v90
	v_fma_f32 v91, -v89, v92, v91
	v_div_fmas_f32 v91, v91, v90, v92
	v_div_fixup_f32 v91, v91, v88, v86
	v_mul_f32_e32 v99, 0xbfb8aa3b, v87
	v_exp_f32_e32 v99, v99
	s_nop 0
	v_add_f32_e32 v94, 1.0, v99
	v_div_scale_f32 v95, s[12:13], v94, v94, v87
	v_rcp_f32_e32 v96, v95
	s_nop 0
	v_fma_f32 v99, -v95, v96, 1.0
	v_fmac_f32_e32 v96, v99, v96
	v_div_scale_f32 v97, vcc, v87, v94, v87
	v_mul_f32_e32 v98, v97, v96
	v_fma_f32 v99, -v95, v98, v97
	v_fmac_f32_e32 v98, v99, v96
	v_fma_f32 v97, -v95, v98, v97
	v_div_fmas_f32 v97, v97, v96, v98
	v_div_fixup_f32 v97, v97, v94, v87
	v_cvt_pk_bf16_f32 v107, v91, v97
	s_lshl_b32 s22, s17, 12
	s_add_u32 s22, s4, s22
	s_addc_u32 s23, s5, 0
	s_add_u32 s17, s17, 0x200
	global_store_dwordx4 v194, v[104:107], s[22:23]
	s_and_b32 s20, s16, 63
	s_bfe_u32 s26, s16, 0x50006
	s_mov_b32 s18, 0x1ff
	s_cmp_eq_u32 s20, 0
	s_cselect_b32 s21, 0x49, 0
	s_andn2_b32 s18, s18, s21
	s_cmp_eq_u32 s20, 63
	s_cselect_b32 s21, 0x124, 0
	s_andn2_b32 s18, s18, s21
	s_cmp_eq_u32 s26, 0
	s_cselect_b32 s21, 0x7, 0
	s_andn2_b32 s18, s18, s21
	s_cmp_eq_u32 s26, 31
	s_cselect_b32 s21, 0x1c0, 0
	s_andn2_b32 s18, s18, s21
	s_mul_i32 s22, s16, 0x3000
	s_mul_hi_u32 s23, s16, 0x3000
	s_add_u32 s22, s0, s22
	s_addc_u32 s23, s1, s23
	s_sub_u32 s22, s22, 0xc3000
	s_subb_u32 s23, s23, 0
	s_bitcmp1_b32 s18, 0
	s_cselect_b32 s24, 0x0, s27
	s_add_u32 s74, s22, s24
	s_addc_u32 s75, s23, 0
	global_load_dwordx4 v[120:123], v194, s[74:75]
	s_bitcmp1_b32 s18, 1
	s_cselect_b32 s24, 0x3000, s27
	s_add_u32 s76, s22, s24
	s_addc_u32 s77, s23, 0
	global_load_dwordx4 v[124:127], v194, s[76:77]
	s_bitcmp1_b32 s18, 2
	s_cselect_b32 s24, 0x6000, s27
	s_add_u32 s78, s22, s24
	s_addc_u32 s79, s23, 0
	global_load_dwordx4 v[128:131], v194, s[78:79]
	s_bitcmp1_b32 s18, 3
	s_cselect_b32 s24, 0xc0000, s27
	s_add_u32 s80, s22, s24
	s_addc_u32 s81, s23, 0
	global_load_dwordx4 v[132:135], v194, s[80:81]
	s_bitcmp1_b32 s18, 4
	s_cselect_b32 s24, 0xc3000, s27
	s_add_u32 s82, s22, s24
	s_addc_u32 s83, s23, 0
	global_load_dwordx4 v[136:139], v194, s[82:83]
	s_bitcmp1_b32 s18, 5
	s_cselect_b32 s24, 0xc6000, s27
	s_add_u32 s84, s22, s24
	s_addc_u32 s85, s23, 0
	global_load_dwordx4 v[140:143], v194, s[84:85]
	s_bitcmp1_b32 s18, 6
	s_cselect_b32 s24, 0x180000, s27
	s_add_u32 s86, s22, s24
	s_addc_u32 s87, s23, 0
	global_load_dwordx4 v[144:147], v194, s[86:87]
	s_bitcmp1_b32 s18, 7
	s_cselect_b32 s24, 0x183000, s27
	s_add_u32 s88, s22, s24
	s_addc_u32 s89, s23, 0
	global_load_dwordx4 v[148:151], v194, s[88:89]
	s_bitcmp1_b32 s18, 8
	s_cselect_b32 s24, 0x186000, s27
	s_add_u32 s90, s22, s24
	s_addc_u32 s91, s23, 0
	global_load_dwordx4 v[152:155], v194, s[90:91]
	s_add_u32 s16, s16, 0x200
	s_waitcnt vmcnt(10)
	v_mov_b32_e32 v80, v112
	v_mov_b32_e32 v81, v113
	v_mov_b32_e32 v82, v114
	v_mov_b32_e32 v83, v115
	v_mov_b32_e32 v84, v116
	v_mov_b32_e32 v85, v117
	v_mov_b32_e32 v86, v118
	v_mov_b32_e32 v87, v119
	s_bitcmp0_b32 s19, 0
	s_cbranch_scc1 .Lcv_skip_34
	v_lshlrev_b32_e32 v88, 16, v156
	v_and_b32_e32 v89, 0xffff0000, v156
	v_lshlrev_b32_e32 v90, 16, v157
	v_and_b32_e32 v91, 0xffff0000, v157
	v_lshlrev_b32_e32 v92, 16, v158
	v_and_b32_e32 v93, 0xffff0000, v158
	v_lshlrev_b32_e32 v94, 16, v159
	v_and_b32_e32 v95, 0xffff0000, v159
	v_fmac_f32_e32 v80, v0, v88
	v_fmac_f32_e32 v81, v1, v89
	v_fmac_f32_e32 v82, v2, v90
	v_fmac_f32_e32 v83, v3, v91
	v_fmac_f32_e32 v84, v4, v92
	v_fmac_f32_e32 v85, v5, v93
	v_fmac_f32_e32 v86, v6, v94
	v_fmac_f32_e32 v87, v7, v95
.Lcv_skip_34:
	s_bitcmp0_b32 s19, 1
	s_cbranch_scc1 .Lcv_skip_35
	v_lshlrev_b32_e32 v88, 16, v160
	v_and_b32_e32 v89, 0xffff0000, v160
	v_lshlrev_b32_e32 v90, 16, v161
	v_and_b32_e32 v91, 0xffff0000, v161
	v_lshlrev_b32_e32 v92, 16, v162
	v_and_b32_e32 v93, 0xffff0000, v162
	v_lshlrev_b32_e32 v94, 16, v163
	v_and_b32_e32 v95, 0xffff0000, v163
	v_fmac_f32_e32 v80, v8, v88
	v_fmac_f32_e32 v81, v9, v89
	v_fmac_f32_e32 v82, v10, v90
	v_fmac_f32_e32 v83, v11, v91
	v_fmac_f32_e32 v84, v12, v92
	v_fmac_f32_e32 v85, v13, v93
	v_fmac_f32_e32 v86, v14, v94
	v_fmac_f32_e32 v87, v15, v95
.Lcv_skip_35:
	s_bitcmp0_b32 s19, 2
	s_cbranch_scc1 .Lcv_skip_36
	v_lshlrev_b32_e32 v88, 16, v164
	v_and_b32_e32 v89, 0xffff0000, v164
	v_lshlrev_b32_e32 v90, 16, v165
	v_and_b32_e32 v91, 0xffff0000, v165
	v_lshlrev_b32_e32 v92, 16, v166
	v_and_b32_e32 v93, 0xffff0000, v166
	v_lshlrev_b32_e32 v94, 16, v167
	v_and_b32_e32 v95, 0xffff0000, v167
	v_fmac_f32_e32 v80, v16, v88
	v_fmac_f32_e32 v81, v17, v89
	v_fmac_f32_e32 v82, v18, v90
	v_fmac_f32_e32 v83, v19, v91
	v_fmac_f32_e32 v84, v20, v92
	v_fmac_f32_e32 v85, v21, v93
	v_fmac_f32_e32 v86, v22, v94
	v_fmac_f32_e32 v87, v23, v95
.Lcv_skip_36:
	s_bitcmp0_b32 s19, 3
	s_cbranch_scc1 .Lcv_skip_37
	v_lshlrev_b32_e32 v88, 16, v168
	v_and_b32_e32 v89, 0xffff0000, v168
	v_lshlrev_b32_e32 v90, 16, v169
	v_and_b32_e32 v91, 0xffff0000, v169
	v_lshlrev_b32_e32 v92, 16, v170
	v_and_b32_e32 v93, 0xffff0000, v170
	v_lshlrev_b32_e32 v94, 16, v171
	v_and_b32_e32 v95, 0xffff0000, v171
	v_fmac_f32_e32 v80, v24, v88
	v_fmac_f32_e32 v81, v25, v89
	v_fmac_f32_e32 v82, v26, v90
	v_fmac_f32_e32 v83, v27, v91
	v_fmac_f32_e32 v84, v28, v92
	v_fmac_f32_e32 v85, v29, v93
	v_fmac_f32_e32 v86, v30, v94
	v_fmac_f32_e32 v87, v31, v95
.Lcv_skip_37:
	s_bitcmp0_b32 s19, 4
	s_cbranch_scc1 .Lcv_skip_38
	v_lshlrev_b32_e32 v88, 16, v172
	v_and_b32_e32 v89, 0xffff0000, v172
	v_lshlrev_b32_e32 v90, 16, v173
	v_and_b32_e32 v91, 0xffff0000, v173
	v_lshlrev_b32_e32 v92, 16, v174
	v_and_b32_e32 v93, 0xffff0000, v174
	v_lshlrev_b32_e32 v94, 16, v175
	v_and_b32_e32 v95, 0xffff0000, v175
	v_fmac_f32_e32 v80, v32, v88
	v_fmac_f32_e32 v81, v33, v89
	v_fmac_f32_e32 v82, v34, v90
	v_fmac_f32_e32 v83, v35, v91
	v_fmac_f32_e32 v84, v36, v92
	v_fmac_f32_e32 v85, v37, v93
	v_fmac_f32_e32 v86, v38, v94
	v_fmac_f32_e32 v87, v39, v95
.Lcv_skip_38:
	s_bitcmp0_b32 s19, 5
	s_cbranch_scc1 .Lcv_skip_39
	v_lshlrev_b32_e32 v88, 16, v176
	v_and_b32_e32 v89, 0xffff0000, v176
	v_lshlrev_b32_e32 v90, 16, v177
	v_and_b32_e32 v91, 0xffff0000, v177
	v_lshlrev_b32_e32 v92, 16, v178
	v_and_b32_e32 v93, 0xffff0000, v178
	v_lshlrev_b32_e32 v94, 16, v179
	v_and_b32_e32 v95, 0xffff0000, v179
	v_fmac_f32_e32 v80, v40, v88
	v_fmac_f32_e32 v81, v41, v89
	v_fmac_f32_e32 v82, v42, v90
	v_fmac_f32_e32 v83, v43, v91
	v_fmac_f32_e32 v84, v44, v92
	v_fmac_f32_e32 v85, v45, v93
	v_fmac_f32_e32 v86, v46, v94
	v_fmac_f32_e32 v87, v47, v95
.Lcv_skip_39:
	s_bitcmp0_b32 s19, 6
	s_cbranch_scc1 .Lcv_skip_40
	v_lshlrev_b32_e32 v88, 16, v180
	v_and_b32_e32 v89, 0xffff0000, v180
	v_lshlrev_b32_e32 v90, 16, v181
	v_and_b32_e32 v91, 0xffff0000, v181
	v_lshlrev_b32_e32 v92, 16, v182
	v_and_b32_e32 v93, 0xffff0000, v182
	v_lshlrev_b32_e32 v94, 16, v183
	v_and_b32_e32 v95, 0xffff0000, v183
	v_fmac_f32_e32 v80, v48, v88
	v_fmac_f32_e32 v81, v49, v89
	v_fmac_f32_e32 v82, v50, v90
	v_fmac_f32_e32 v83, v51, v91
	v_fmac_f32_e32 v84, v52, v92
	v_fmac_f32_e32 v85, v53, v93
	v_fmac_f32_e32 v86, v54, v94
	v_fmac_f32_e32 v87, v55, v95
.Lcv_skip_40:
	s_bitcmp0_b32 s19, 7
	s_cbranch_scc1 .Lcv_skip_41
	v_lshlrev_b32_e32 v88, 16, v186
	v_and_b32_e32 v89, 0xffff0000, v186
	v_lshlrev_b32_e32 v90, 16, v187
	v_and_b32_e32 v91, 0xffff0000, v187
	v_lshlrev_b32_e32 v92, 16, v188
	v_and_b32_e32 v93, 0xffff0000, v188
	v_lshlrev_b32_e32 v94, 16, v189
	v_and_b32_e32 v95, 0xffff0000, v189
	v_fmac_f32_e32 v80, v56, v88
	v_fmac_f32_e32 v81, v57, v89
	v_fmac_f32_e32 v82, v58, v90
	v_fmac_f32_e32 v83, v59, v91
	v_fmac_f32_e32 v84, v60, v92
	v_fmac_f32_e32 v85, v61, v93
	v_fmac_f32_e32 v86, v62, v94
	v_fmac_f32_e32 v87, v63, v95
.Lcv_skip_41:
	s_bitcmp0_b32 s19, 8
	s_cbranch_scc1 .Lcv_skip_42
	v_lshlrev_b32_e32 v88, 16, v190
	v_and_b32_e32 v89, 0xffff0000, v190
	v_lshlrev_b32_e32 v90, 16, v191
	v_and_b32_e32 v91, 0xffff0000, v191
	v_lshlrev_b32_e32 v92, 16, v192
	v_and_b32_e32 v93, 0xffff0000, v192
	v_lshlrev_b32_e32 v94, 16, v193
	v_and_b32_e32 v95, 0xffff0000, v193
	v_fmac_f32_e32 v80, v64, v88
	v_fmac_f32_e32 v81, v65, v89
	v_fmac_f32_e32 v82, v66, v90
	v_fmac_f32_e32 v83, v67, v91
	v_fmac_f32_e32 v84, v68, v92
	v_fmac_f32_e32 v85, v69, v93
	v_fmac_f32_e32 v86, v70, v94
	v_fmac_f32_e32 v87, v71, v95

.Lcv_skip_87:
	v_mul_f32_e32 v93, 0xbfb8aa3b, v80
	v_exp_f32_e32 v93, v93
	s_nop 0
	v_add_f32_e32 v88, 1.0, v93
	v_div_scale_f32 v89, s[12:13], v88, v88, v80
	v_rcp_f32_e32 v90, v89
	s_nop 0
	v_fma_f32 v93, -v89, v90, 1.0
	v_fmac_f32_e32 v90, v93, v90
	v_div_scale_f32 v91, vcc, v80, v88, v80
	v_mul_f32_e32 v92, v91, v90
	v_fma_f32 v93, -v89, v92, v91
	v_fmac_f32_e32 v92, v93, v90
	v_fma_f32 v91, -v89, v92, v91
	v_div_fmas_f32 v91, v91, v90, v92
	v_div_fixup_f32 v91, v91, v88, v80
	v_mul_f32_e32 v99, 0xbfb8aa3b, v81
	v_exp_f32_e32 v99, v99
	s_nop 0
	v_add_f32_e32 v94, 1.0, v99
	v_div_scale_f32 v95, s[12:13], v94, v94, v81
	v_rcp_f32_e32 v96, v95
	s_nop 0
	v_fma_f32 v99, -v95, v96, 1.0
	v_fmac_f32_e32 v96, v99, v96
	v_div_scale_f32 v97, vcc, v81, v94, v81
	v_mul_f32_e32 v98, v97, v96
	v_fma_f32 v99, -v95, v98, v97
	v_fmac_f32_e32 v98, v99, v96
	v_fma_f32 v97, -v95, v98, v97
	v_div_fmas_f32 v97, v97, v96, v98
	v_div_fixup_f32 v97, v97, v94, v81
	v_cvt_pk_bf16_f32 v104, v91, v97
	v_mul_f32_e32 v93, 0xbfb8aa3b, v82
	v_exp_f32_e32 v93, v93
	s_nop 0
	v_add_f32_e32 v88, 1.0, v93
	v_div_scale_f32 v89, s[12:13], v88, v88, v82
	v_rcp_f32_e32 v90, v89
	s_nop 0
	v_fma_f32 v93, -v89, v90, 1.0
	v_fmac_f32_e32 v90, v93, v90
	v_div_scale_f32 v91, vcc, v82, v88, v82
	v_mul_f32_e32 v92, v91, v90
	v_fma_f32 v93, -v89, v92, v91
	v_fmac_f32_e32 v92, v93, v90
	v_fma_f32 v91, -v89, v92, v91
	v_div_fmas_f32 v91, v91, v90, v92
	v_div_fixup_f32 v91, v91, v88, v82
	v_mul_f32_e32 v99, 0xbfb8aa3b, v83
	v_exp_f32_e32 v99, v99
	s_nop 0
	v_add_f32_e32 v94, 1.0, v99
	v_div_scale_f32 v95, s[12:13], v94, v94, v83
	v_rcp_f32_e32 v96, v95
	s_nop 0
	v_fma_f32 v99, -v95, v96, 1.0
	v_fmac_f32_e32 v96, v99, v96
	v_div_scale_f32 v97, vcc, v83, v94, v83
	v_mul_f32_e32 v98, v97, v96
	v_fma_f32 v99, -v95, v98, v97
	v_fmac_f32_e32 v98, v99, v96
	v_fma_f32 v97, -v95, v98, v97
	v_div_fmas_f32 v97, v97, v96, v98
	v_div_fixup_f32 v97, v97, v94, v83
	v_cvt_pk_bf16_f32 v105, v91, v97
	v_mul_f32_e32 v93, 0xbfb8aa3b, v84
	v_exp_f32_e32 v93, v93
	s_nop 0
	v_add_f32_e32 v88, 1.0, v93
	v_div_scale_f32 v89, s[12:13], v88, v88, v84
	v_rcp_f32_e32 v90, v89
	s_nop 0
	v_fma_f32 v93, -v89, v90, 1.0
	v_fmac_f32_e32 v90, v93, v90
	v_div_scale_f32 v91, vcc, v84, v88, v84
	v_mul_f32_e32 v92, v91, v90
	v_fma_f32 v93, -v89, v92, v91
	v_fmac_f32_e32 v92, v93, v90
	v_fma_f32 v91, -v89, v92, v91
	v_div_fmas_f32 v91, v91, v90, v92
	v_div_fixup_f32 v91, v91, v88, v84
	v_mul_f32_e32 v99, 0xbfb8aa3b, v85
	v_exp_f32_e32 v99, v99
	s_nop 0
	v_add_f32_e32 v94, 1.0, v99
	v_div_scale_f32 v95, s[12:13], v94, v94, v85
	v_rcp_f32_e32 v96, v95
	s_nop 0
	v_fma_f32 v99, -v95, v96, 1.0
	v_fmac_f32_e32 v96, v99, v96
	v_div_scale_f32 v97, vcc, v85, v94, v85
	v_mul_f32_e32 v98, v97, v96
	v_fma_f32 v99, -v95, v98, v97
	v_fmac_f32_e32 v98, v99, v96
	v_fma_f32 v97, -v95, v98, v97
	v_div_fmas_f32 v97, v97, v96, v98
	v_div_fixup_f32 v97, v97, v94, v85
	v_cvt_pk_bf16_f32 v106, v91, v97
	v_mul_f32_e32 v93, 0xbfb8aa3b, v86
	v_exp_f32_e32 v93, v93
	s_nop 0
	v_add_f32_e32 v88, 1.0, v93
	v_div_scale_f32 v89, s[12:13], v88, v88, v86
	v_rcp_f32_e32 v90, v89
	s_nop 0
	v_fma_f32 v93, -v89, v90, 1.0
	v_fmac_f32_e32 v90, v93, v90
	v_div_scale_f32 v91, vcc, v86, v88, v86
	v_mul_f32_e32 v92, v91, v90
	v_fma_f32 v93, -v89, v92, v91
	v_fmac_f32_e32 v92, v93, v90
	v_fma_f32 v91, -v89, v92, v91
	v_div_fmas_f32 v91, v91, v90, v92
	v_div_fixup_f32 v91, v91, v88, v86
	v_mul_f32_e32 v99, 0xbfb8aa3b, v87
	v_exp_f32_e32 v99, v99
	s_nop 0
	v_add_f32_e32 v94, 1.0, v99
	v_div_scale_f32 v95, s[12:13], v94, v94, v87
	v_rcp_f32_e32 v96, v95
	s_nop 0
	v_fma_f32 v99, -v95, v96, 1.0
	v_fmac_f32_e32 v96, v99, v96
	v_div_scale_f32 v97, vcc, v87, v94, v87
	v_mul_f32_e32 v98, v97, v96
	v_fma_f32 v99, -v95, v98, v97
	v_fmac_f32_e32 v98, v99, v96
	v_fma_f32 v97, -v95, v98, v97
	v_div_fmas_f32 v97, v97, v96, v98
	v_div_fixup_f32 v97, v97, v94, v87
	v_cvt_pk_bf16_f32 v107, v91, v97
	s_lshl_b32 s22, s17, 12
	s_add_u32 s22, s4, s22
	s_addc_u32 s23, s5, 0
	s_add_u32 s17, s17, 0x200
	global_store_dwordx4 v194, v[104:107], s[22:23]
	s_waitcnt vmcnt(1)
	v_mov_b32_e32 v80, v112
	v_mov_b32_e32 v81, v113
	v_mov_b32_e32 v82, v114
	v_mov_b32_e32 v83, v115
	v_mov_b32_e32 v84, v116
	v_mov_b32_e32 v85, v117
	v_mov_b32_e32 v86, v118
	v_mov_b32_e32 v87, v119
	s_bitcmp0_b32 s19, 0
	s_cbranch_scc1 .Lcv_skip_88
	v_lshlrev_b32_e32 v88, 16, v156
	v_and_b32_e32 v89, 0xffff0000, v156
	v_lshlrev_b32_e32 v90, 16, v157
	v_and_b32_e32 v91, 0xffff0000, v157
	v_lshlrev_b32_e32 v92, 16, v158
	v_and_b32_e32 v93, 0xffff0000, v158
	v_lshlrev_b32_e32 v94, 16, v159
	v_and_b32_e32 v95, 0xffff0000, v159
	v_fmac_f32_e32 v80, v0, v88
	v_fmac_f32_e32 v81, v1, v89
	v_fmac_f32_e32 v82, v2, v90
	v_fmac_f32_e32 v83, v3, v91
	v_fmac_f32_e32 v84, v4, v92
	v_fmac_f32_e32 v85, v5, v93
	v_fmac_f32_e32 v86, v6, v94
	v_fmac_f32_e32 v87, v7, v95

.Lcv_skip_96:
	v_mul_f32_e32 v93, 0xbfb8aa3b, v80
	v_exp_f32_e32 v93, v93
	s_nop 0
	v_add_f32_e32 v88, 1.0, v93
	v_div_scale_f32 v89, s[12:13], v88, v88, v80
	v_rcp_f32_e32 v90, v89
	s_nop 0
	v_fma_f32 v93, -v89, v90, 1.0
	v_fmac_f32_e32 v90, v93, v90
	v_div_scale_f32 v91, vcc, v80, v88, v80
	v_mul_f32_e32 v92, v91, v90
	v_fma_f32 v93, -v89, v92, v91
	v_fmac_f32_e32 v92, v93, v90
	v_fma_f32 v91, -v89, v92, v91
	v_div_fmas_f32 v91, v91, v90, v92
	v_div_fixup_f32 v91, v91, v88, v80
	v_mul_f32_e32 v99, 0xbfb8aa3b, v81
	v_exp_f32_e32 v99, v99
	s_nop 0
	v_add_f32_e32 v94, 1.0, v99
	v_div_scale_f32 v95, s[12:13], v94, v94, v81
	v_rcp_f32_e32 v96, v95
	s_nop 0
	v_fma_f32 v99, -v95, v96, 1.0
	v_fmac_f32_e32 v96, v99, v96
	v_div_scale_f32 v97, vcc, v81, v94, v81
	v_mul_f32_e32 v98, v97, v96
	v_fma_f32 v99, -v95, v98, v97
	v_fmac_f32_e32 v98, v99, v96
	v_fma_f32 v97, -v95, v98, v97
	v_div_fmas_f32 v97, v97, v96, v98
	v_div_fixup_f32 v97, v97, v94, v81
	v_cvt_pk_bf16_f32 v104, v91, v97
	v_mul_f32_e32 v93, 0xbfb8aa3b, v82
	v_exp_f32_e32 v93, v93
	s_nop 0
	v_add_f32_e32 v88, 1.0, v93
	v_div_scale_f32 v89, s[12:13], v88, v88, v82
	v_rcp_f32_e32 v90, v89
	s_nop 0
	v_fma_f32 v93, -v89, v90, 1.0
	v_fmac_f32_e32 v90, v93, v90
	v_div_scale_f32 v91, vcc, v82, v88, v82
	v_mul_f32_e32 v92, v91, v90
	v_fma_f32 v93, -v89, v92, v91
	v_fmac_f32_e32 v92, v93, v90
	v_fma_f32 v91, -v89, v92, v91
	v_div_fmas_f32 v91, v91, v90, v92
	v_div_fixup_f32 v91, v91, v88, v82
	v_mul_f32_e32 v99, 0xbfb8aa3b, v83
	v_exp_f32_e32 v99, v99
	s_nop 0
	v_add_f32_e32 v94, 1.0, v99
	v_div_scale_f32 v95, s[12:13], v94, v94, v83
	v_rcp_f32_e32 v96, v95
	s_nop 0
	v_fma_f32 v99, -v95, v96, 1.0
	v_fmac_f32_e32 v96, v99, v96
	v_div_scale_f32 v97, vcc, v83, v94, v83
	v_mul_f32_e32 v98, v97, v96
	v_fma_f32 v99, -v95, v98, v97
	v_fmac_f32_e32 v98, v99, v96
	v_fma_f32 v97, -v95, v98, v97
	v_div_fmas_f32 v97, v97, v96, v98
	v_div_fixup_f32 v97, v97, v94, v83
	v_cvt_pk_bf16_f32 v105, v91, v97
	v_mul_f32_e32 v93, 0xbfb8aa3b, v84
	v_exp_f32_e32 v93, v93
	s_nop 0
	v_add_f32_e32 v88, 1.0, v93
	v_div_scale_f32 v89, s[12:13], v88, v88, v84
	v_rcp_f32_e32 v90, v89
	s_nop 0
	v_fma_f32 v93, -v89, v90, 1.0
	v_fmac_f32_e32 v90, v93, v90
	v_div_scale_f32 v91, vcc, v84, v88, v84
	v_mul_f32_e32 v92, v91, v90
	v_fma_f32 v93, -v89, v92, v91
	v_fmac_f32_e32 v92, v93, v90
	v_fma_f32 v91, -v89, v92, v91
	v_div_fmas_f32 v91, v91, v90, v92
	v_div_fixup_f32 v91, v91, v88, v84
	v_mul_f32_e32 v99, 0xbfb8aa3b, v85
	v_exp_f32_e32 v99, v99
	s_nop 0
	v_add_f32_e32 v94, 1.0, v99
	v_div_scale_f32 v95, s[12:13], v94, v94, v85
	v_rcp_f32_e32 v96, v95
	s_nop 0
	v_fma_f32 v99, -v95, v96, 1.0
	v_fmac_f32_e32 v96, v99, v96
	v_div_scale_f32 v97, vcc, v85, v94, v85
	v_mul_f32_e32 v98, v97, v96
	v_fma_f32 v99, -v95, v98, v97
	v_fmac_f32_e32 v98, v99, v96
	v_fma_f32 v97, -v95, v98, v97
	v_div_fmas_f32 v97, v97, v96, v98
	v_div_fixup_f32 v97, v97, v94, v85
	v_cvt_pk_bf16_f32 v106, v91, v97
	v_mul_f32_e32 v93, 0xbfb8aa3b, v86
	v_exp_f32_e32 v93, v93
	s_nop 0
	v_add_f32_e32 v88, 1.0, v93
	v_div_scale_f32 v89, s[12:13], v88, v88, v86
	v_rcp_f32_e32 v90, v89
	s_nop 0
	v_fma_f32 v93, -v89, v90, 1.0
	v_fmac_f32_e32 v90, v93, v90
	v_div_scale_f32 v91, vcc, v86, v88, v86
	v_mul_f32_e32 v92, v91, v90
	v_fma_f32 v93, -v89, v92, v91
	v_fmac_f32_e32 v92, v93, v90
	v_fma_f32 v91, -v89, v92, v91
	v_div_fmas_f32 v91, v91, v90, v92
	v_div_fixup_f32 v91, v91, v88, v86
	v_mul_f32_e32 v99, 0xbfb8aa3b, v87
	v_exp_f32_e32 v99, v99
	s_nop 0
	v_add_f32_e32 v94, 1.0, v99
	v_div_scale_f32 v95, s[12:13], v94, v94, v87
	v_rcp_f32_e32 v96, v95
	s_nop 0
	v_fma_f32 v99, -v95, v96, 1.0
	v_fmac_f32_e32 v96, v99, v96
	v_div_scale_f32 v97, vcc, v87, v94, v87
	v_mul_f32_e32 v98, v97, v96
	v_fma_f32 v99, -v95, v98, v97
	v_fmac_f32_e32 v98, v99, v96
	v_fma_f32 v97, -v95, v98, v97
	v_div_fmas_f32 v97, v97, v96, v98
	v_div_fixup_f32 v97, v97, v94, v87
	v_cvt_pk_bf16_f32 v107, v91, v97
	s_lshl_b32 s22, s17, 12
	s_add_u32 s22, s4, s22
	s_addc_u32 s23, s5, 0
	s_add_u32 s17, s17, 0x200
	global_store_dwordx4 v194, v[104:107], s[22:23]
